# attention-B: removed the end-of-step barrier by double-buffering the P-exchange slots by step parity (second copy in 16 KiB static LDS)
# speedup vs baseline: 1.0153x; 1.0130x over previous
; __device__ __forceinline__ void lds_barrier() { asm volatile("s_waitcnt lgkmcnt(0)" ::: "memory"); __builtin_amdgcn_s_barrier(); asm volatile("" ::: "memory"); }
; __device__ void attn_pair_block(LAS unsigned char* lds, const bf16_t* Qp, const bf16_t* Kp, const bf16_t* Vp, int qb, bf16_t* outp, const float negMB) {
;     ...
;         lds_barrier();
;     }
.Lpb_tail:
	s_add_i32 s17, s17, 64
	s_cmp_eq_u32 s22, s20
	s_cbranch_scc1 .LBB0_812

; #define LAS __attribute__((address_space(3)))
; __device__ __forceinline__ unsigned cvt_pk_bf16(float lo, float hi) { unsigned r; asm volatile("v_cvt_pk_bf16_f32 %0, %1, %2" : "=v"(r) : "v"(lo), "v"(hi)); return r; }
; __device__ void attn_pair_block(LAS unsigned char* lds, const bf16_t* Qp, const bf16_t* Kp, const bf16_t* Vp, int qb, bf16_t* outp, const float negMB) {
;     ...
;             for (int r = 0; r < 16; ++r) s0[r] = fast_exp2(s0[r]);
;             float ls = 0.f;
; #pragma unroll
;             for (int r = 0; r < 16; ++r) ls += s0[r];
;             lrun += ls;
; #pragma unroll
;             for (int s2 = 0; s2 < 2; ++s2) { u32x4 w0;
;                 w0.x = cvt_pk_bf16(s0[8 * s2 + 0], s0[8 * s2 + 1]); w0.y = cvt_pk_bf16(s0[8 * s2 + 2], s0[8 * s2 + 3]); w0.z = cvt_pk_bf16(s0[8 * s2 + 4], s0[8 * s2 + 5]); w0.w = cvt_pk_bf16(s0[8 * s2 + 6], s0[8 * s2 + 7]);
;                 pown[s2] = __builtin_bit_cast(bf16x8, w0); *(LAS u32x4*)(xmine + s2 * 1024) = w0; }
;         }
;         lds_barrier();
;         if (act) {
;             bf16x8 poth[2];
; #pragma unroll
;             for (int s2 = 0; s2 < 2; ++s2) poth[s2] = *(const LAS bf16x8*)(xother + s2 * 1024);
;             __builtin_amdgcn_s_setprio(1);
; #pragma unroll
;             for (int st = 0; st < 2; ++st)
; #pragma unroll
;                 for (int s2 = 0; s2 < 2; ++s2)
; #pragma unroll
;                     for (int d = 0; d < 4; ++d) {
;                         const s16x4 lo = __builtin_amdgcn_ds_read_tr16_b64_v4i16((LAS s16x4*)(vb + vread + (32 * st + 16 * s2) * VP2 + d * 64));
;                         const s16x4 hi = __builtin_amdgcn_ds_read_tr16_b64_v4i16((LAS s16x4*)(vb + vread + (32 * st + 16 * s2 + 8) * VP2 + d * 64));
;                         const bf16x8 vf = __builtin_shufflevector(lo, hi, 0, 1, 2, 3, 4, 5, 6, 7);
;                         const bf16x8 pfr = (st == stw) ? pown[s2] : poth[s2];
;                         o[d] = __builtin_amdgcn_mfma_f32_32x32x16_bf16(vf, pfr, o[d], 0, 0, 0);
;                     }
;             __builtin_amdgcn_sched_group_barrier(0x100, 8, 1);
; #pragma unroll
;             for (int i = 0; i < 16; ++i) { __builtin_amdgcn_sched_group_barrier(0x008, 1, 1); __builtin_amdgcn_sched_group_barrier(0x100, 2, 1); }
;             __builtin_amdgcn_s_setprio(0);
;         }
;         if (j + 1 < nt) PB_LSTORE((j + 1) & 1);
.LBB0_809:
	s_nop 10
	v_exp_f32_e32 v80, v80
	v_exp_f32_e32 v81, v81
	v_exp_f32_e32 v82, v82
	v_exp_f32_e32 v83, v83
	v_exp_f32_e32 v193, v84
	v_add_f32_e32 v84, 0, v80
	v_exp_f32_e32 v194, v85
	v_add_f32_e32 v84, v81, v84
	v_exp_f32_e32 v195, v86
	v_add_f32_e32 v84, v82, v84
	v_exp_f32_e32 v87, v87
	v_add_f32_e32 v84, v83, v84
	v_exp_f32_e32 v88, v88
	v_add_f32_e32 v84, v193, v84
	v_exp_f32_e32 v89, v89
	v_add_f32_e32 v84, v194, v84
	v_exp_f32_e32 v90, v90
	v_add_f32_e32 v84, v195, v84
	v_exp_f32_e32 v91, v91
	v_add_f32_e32 v84, v87, v84
	v_exp_f32_e32 v92, v92
	v_add_f32_e32 v84, v88, v84
	v_exp_f32_e32 v93, v93
	v_add_f32_e32 v84, v89, v84
	v_exp_f32_e32 v94, v94
	v_add_f32_e32 v84, v90, v84
	v_exp_f32_e32 v95, v95
	v_add_f32_e32 v84, v91, v84
	v_add_f32_e32 v84, v92, v84
	v_add_f32_e32 v84, v93, v84
	v_add_f32_e32 v84, v94, v84
	v_add_f32_e32 v196, v95, v84
	v_cvt_pk_bf16_f32 v84, v80, v81
	v_cvt_pk_bf16_f32 v85, v82, v83
	v_cvt_pk_bf16_f32 v86, v193, v194
	s_bitcmp1_b32 s20, 0
	s_cselect_b32 s25, 0x7840, 0
	s_add_i32 s25, s25, s13
	v_add_u32_e32 v193, s25, v163
	v_add_f32_e32 v167, v167, v196
	v_cvt_pk_bf16_f32 v87, v195, v87
	ds_write_b128 v193, v[84:87]
	v_cvt_pk_bf16_f32 v80, v88, v89
	v_cvt_pk_bf16_f32 v81, v90, v91
	v_cvt_pk_bf16_f32 v82, v92, v93
	v_cvt_pk_bf16_f32 v83, v94, v95
	ds_write_b128 v193, v[80:83] offset:1024
.LBB0_810:
	s_waitcnt lgkmcnt(0)
	s_barrier
	global_load_dwordx4 v[128:131], v250, s[100:101]
	global_load_dwordx4 v[136:139], v251, s[100:101]
	s_add_u32 s100, s100, 0x20000
	s_addc_u32 s101, s101, 0
	s_andn2_b64 vcc, exec, s[8:9]
	s_cbranch_vccnz .LBB0_805
	s_bitcmp1_b32 s20, 0
	s_cselect_b32 s25, 0x7840, 0
	s_add_i32 s25, s25, s15
	v_add_u32_e32 v92, s25, v163
	ds_read_b128 v[88:91], v92
	ds_read_b128 v[92:95], v92 offset:1024
	s_setprio 1
	s_add_i32 s8, s14, s23
	s_mul_i32 s24, s12, 0x4800
	s_sub_i32 s25, 0x4800, s24
	v_add_u32_e32 v193, s8, v169
	v_add3_u32 v193, v193, v171, v173
	v_add_u32_e32 v194, s25, v193
	v_add_u32_e32 v193, s24, v193
	ds_read_b64_tr_b16 v[198:199], v193 offset:17408
	ds_read_b64_tr_b16 v[200:201], v193 offset:22016
	ds_read_b64_tr_b16 v[202:203], v193 offset:17472
	ds_read_b64_tr_b16 v[204:205], v193 offset:22080
	ds_read_b64_tr_b16 v[206:207], v193 offset:17536
	ds_read_b64_tr_b16 v[208:209], v193 offset:22144
	ds_read_b64_tr_b16 v[210:211], v193 offset:17600
	ds_read_b64_tr_b16 v[212:213], v193 offset:22208
	s_add_i32 s24, s20, 1
	s_bitcmp1_b32 s24, 0
	s_cselect_b32 s23, 0xd400, 0
	v_add_u32_e32 v242, s23, v162
	v_add_u32_e32 v243, v242, v188
	v_add_u32_e32 v244, v242, v189
	v_add_u32_e32 v245, v242, v190
	v_add_u32_e32 v242, v242, v191
	s_waitcnt lgkmcnt(6)
	v_mfma_f32_32x32x16_bf16 v[64:79], v[198:201], v[84:87], v[64:79]
	ds_read_b64_tr_b16 v[198:199], v193 offset:26624
	ds_read_b64_tr_b16 v[200:201], v193 offset:31232
	s_waitcnt lgkmcnt(6)
	v_mfma_f32_32x32x16_bf16 v[48:63], v[202:205], v[84:87], v[48:63]
	ds_read_b64_tr_b16 v[202:203], v193 offset:26688
	ds_read_b64_tr_b16 v[204:205], v193 offset:31296
	s_waitcnt lgkmcnt(6)
	v_mfma_f32_32x32x16_bf16 v[32:47], v[206:209], v[84:87], v[32:47]
	ds_read_b64_tr_b16 v[206:207], v193 offset:26752
	ds_read_b64_tr_b16 v[208:209], v193 offset:31360
	s_waitcnt vmcnt(5)
	ds_write_b128 v243, v[132:135] offset:17408
	s_waitcnt lgkmcnt(7)
	v_mfma_f32_32x32x16_bf16 v[16:31], v[210:213], v[84:87], v[16:31]
	ds_read_b64_tr_b16 v[210:211], v193 offset:26816
	ds_read_b64_tr_b16 v[212:213], v193 offset:31424
	s_waitcnt lgkmcnt(7)
	v_mfma_f32_32x32x16_bf16 v[64:79], v[198:201], v[80:83], v[64:79]
	ds_read_b64_tr_b16 v[198:199], v194 offset:17408
	ds_read_b64_tr_b16 v[200:201], v194 offset:22016
	s_waitcnt lgkmcnt(7)
	v_mfma_f32_32x32x16_bf16 v[48:63], v[202:205], v[80:83], v[48:63]
	ds_read_b64_tr_b16 v[202:203], v194 offset:17472
	ds_read_b64_tr_b16 v[204:205], v194 offset:22080
	s_waitcnt vmcnt(4)
	ds_write_b128 v244, v[144:147] offset:17408
	s_waitcnt lgkmcnt(8)
	v_mfma_f32_32x32x16_bf16 v[32:47], v[206:209], v[80:83], v[32:47]
	ds_read_b64_tr_b16 v[206:207], v194 offset:17536
	ds_read_b64_tr_b16 v[208:209], v194 offset:22144
	s_waitcnt lgkmcnt(7)
	v_mfma_f32_32x32x16_bf16 v[16:31], v[210:213], v[80:83], v[16:31]
	ds_read_b64_tr_b16 v[210:211], v194 offset:17600
	ds_read_b64_tr_b16 v[212:213], v194 offset:22208
	s_waitcnt lgkmcnt(7)
	v_mfma_f32_32x32x16_bf16 v[64:79], v[198:201], v[88:91], v[64:79]
	ds_read_b64_tr_b16 v[198:199], v194 offset:26624
	ds_read_b64_tr_b16 v[200:201], v194 offset:31232
	s_waitcnt vmcnt(3)
	ds_write_b128 v245, v[140:143] offset:17408
	s_waitcnt lgkmcnt(8)
	v_mfma_f32_32x32x16_bf16 v[48:63], v[202:205], v[88:91], v[48:63]
	ds_read_b64_tr_b16 v[202:203], v194 offset:26688
	ds_read_b64_tr_b16 v[204:205], v194 offset:31296
	s_waitcnt lgkmcnt(7)
	v_mfma_f32_32x32x16_bf16 v[32:47], v[206:209], v[88:91], v[32:47]
	ds_read_b64_tr_b16 v[206:207], v194 offset:26752
	ds_read_b64_tr_b16 v[208:209], v194 offset:31360
	s_waitcnt lgkmcnt(7)
	v_mfma_f32_32x32x16_bf16 v[16:31], v[210:213], v[88:91], v[16:31]
	ds_read_b64_tr_b16 v[210:211], v194 offset:26816
	ds_read_b64_tr_b16 v[212:213], v194 offset:31424
	s_waitcnt vmcnt(2)
	ds_write_b128 v242, v[148:151] offset:17408
	s_waitcnt lgkmcnt(8)
	v_mfma_f32_32x32x16_bf16 v[64:79], v[198:201], v[92:95], v[64:79]
	s_waitcnt lgkmcnt(5)
	v_mfma_f32_32x32x16_bf16 v[48:63], v[202:205], v[92:95], v[48:63]
	s_waitcnt lgkmcnt(3)
	v_mfma_f32_32x32x16_bf16 v[32:47], v[206:209], v[92:95], v[32:47]
	s_waitcnt lgkmcnt(1)
	v_mfma_f32_32x32x16_bf16 v[16:31], v[210:213], v[92:95], v[16:31]
	s_setprio 0
	s_add_i32 s20, s20, 1
	s_branch .Lpb_tail

; #define LAS __attribute__((address_space(3)))
; __device__ __forceinline__ unsigned cvt_pk_bf16(float lo, float hi) { unsigned r; asm volatile("v_cvt_pk_bf16_f32 %0, %1, %2" : "=v"(r) : "v"(lo), "v"(hi)); return r; }
; __device__ __forceinline__ float fast_exp2(float x) { return __builtin_amdgcn_exp2f(x); }
; __device__ void attn_pair_block(LAS unsigned char* lds, const bf16_t* Qp, const bf16_t* Kp, const bf16_t* Vp, int qb, bf16_t* outp, const float negMB) {
;     ...
;             for (int r = 0; r < 16; ++r) s0[r] = fast_exp2(s0[r]);
;             float ls = 0.f;
; #pragma unroll
;             for (int r = 0; r < 16; ++r) ls += s0[r];
;             lrun += ls;
; #pragma unroll
;             for (int s2 = 0; s2 < 2; ++s2) { u32x4 w0;
;                 w0.x = cvt_pk_bf16(s0[8 * s2 + 0], s0[8 * s2 + 1]); w0.y = cvt_pk_bf16(s0[8 * s2 + 2], s0[8 * s2 + 3]); w0.z = cvt_pk_bf16(s0[8 * s2 + 4], s0[8 * s2 + 5]); w0.w = cvt_pk_bf16(s0[8 * s2 + 6], s0[8 * s2 + 7]);
;                 pown[s2] = __builtin_bit_cast(bf16x8, w0); *(LAS u32x4*)(xmine + s2 * 1024) = w0; }
;         }
;         lds_barrier();
;         if (act) {
;             bf16x8 poth[2];
; #pragma unroll
;             for (int s2 = 0; s2 < 2; ++s2) poth[s2] = *(const LAS bf16x8*)(xother + s2 * 1024);
;             __builtin_amdgcn_s_setprio(1);
; #pragma unroll
;             for (int st = 0; st < 2; ++st)
; #pragma unroll
;                 for (int s2 = 0; s2 < 2; ++s2)
; #pragma unroll
;                     for (int d = 0; d < 4; ++d) {
;                         const s16x4 lo = __builtin_amdgcn_ds_read_tr16_b64_v4i16((LAS s16x4*)(vb + vread + (32 * st + 16 * s2) * VP2 + d * 64));
;                         const s16x4 hi = __builtin_amdgcn_ds_read_tr16_b64_v4i16((LAS s16x4*)(vb + vread + (32 * st + 16 * s2 + 8) * VP2 + d * 64));
;                         const bf16x8 vf = __builtin_shufflevector(lo, hi, 0, 1, 2, 3, 4, 5, 6, 7);
;                         const bf16x8 pfr = (st == stw) ? pown[s2] : poth[s2];
;                         o[d] = __builtin_amdgcn_mfma_f32_32x32x16_bf16(vf, pfr, o[d], 0, 0, 0);
;                     }
;             __builtin_amdgcn_sched_group_barrier(0x100, 8, 1);
; #pragma unroll
;             for (int i = 0; i < 16; ++i) { __builtin_amdgcn_sched_group_barrier(0x008, 1, 1); __builtin_amdgcn_sched_group_barrier(0x100, 2, 1); }
;             __builtin_amdgcn_s_setprio(0);
;         }
.LBB0_815:
	s_nop 10
	v_exp_f32_e32 v80, v80
	v_exp_f32_e32 v81, v81
	v_exp_f32_e32 v82, v82
	v_exp_f32_e32 v83, v83
	v_exp_f32_e32 v96, v84
	v_add_f32_e32 v84, 0, v80
	v_exp_f32_e32 v97, v85
	v_add_f32_e32 v84, v81, v84
	v_exp_f32_e32 v98, v86
	v_add_f32_e32 v84, v82, v84
	v_exp_f32_e32 v87, v87
	v_add_f32_e32 v84, v83, v84
	v_exp_f32_e32 v88, v88
	v_add_f32_e32 v84, v96, v84
	v_exp_f32_e32 v89, v89
	v_add_f32_e32 v84, v97, v84
	v_exp_f32_e32 v90, v90
	v_add_f32_e32 v84, v98, v84
	v_exp_f32_e32 v91, v91
	v_add_f32_e32 v84, v87, v84
	v_exp_f32_e32 v92, v92
	v_add_f32_e32 v84, v88, v84
	v_exp_f32_e32 v93, v93
	v_add_f32_e32 v84, v89, v84
	v_exp_f32_e32 v94, v94
	v_add_f32_e32 v84, v90, v84
	v_exp_f32_e32 v95, v95
	v_add_f32_e32 v84, v91, v84
	v_add_f32_e32 v84, v92, v84
	v_add_f32_e32 v84, v93, v84
	v_add_f32_e32 v84, v94, v84
	v_add_f32_e32 v99, v95, v84
	v_cvt_pk_bf16_f32 v84, v80, v81
	v_cvt_pk_bf16_f32 v85, v82, v83
	v_cvt_pk_bf16_f32 v86, v96, v97
	s_bitcmp1_b32 s20, 0
	s_cselect_b32 s25, 0x7840, 0
	s_add_i32 s25, s25, s13
	v_add_u32_e32 v96, s25, v163
	v_add_f32_e32 v167, v167, v99
	v_cvt_pk_bf16_f32 v87, v98, v87
	ds_write_b128 v96, v[84:87]
	v_cvt_pk_bf16_f32 v80, v88, v89
	v_cvt_pk_bf16_f32 v81, v90, v91
	v_cvt_pk_bf16_f32 v82, v92, v93
	v_cvt_pk_bf16_f32 v83, v94, v95
	ds_write_b128 v96, v[80:83] offset:1024
.LBB0_816:
	s_waitcnt lgkmcnt(0)
	s_barrier
	s_andn2_b64 vcc, exec, s[8:9]
	v_add_u32_e32 v88, s15, v163
	s_cbranch_vccnz .LBB0_614
	s_bitcmp1_b32 s20, 0
	s_cselect_b32 s25, 0x7840, 0
	v_add_u32_e32 v89, s25, v88
	ds_read_b128 v[90:93], v89
	ds_read_b128 v[94:97], v89 offset:1024
	s_setprio 1
	s_add_i32 s14, s14, s23
	v_add_u32_e32 v89, s14, v169
	v_add3_u32 v89, v89, v171, v173
	ds_read_b64_tr_b16 v[102:103], v89 offset:17408
	ds_read_b64_tr_b16 v[104:105], v89 offset:22016
	ds_read_b64_tr_b16 v[106:107], v89 offset:17472
	ds_read_b64_tr_b16 v[108:109], v89 offset:22080
	ds_read_b64_tr_b16 v[110:111], v89 offset:17536
	ds_read_b64_tr_b16 v[112:113], v89 offset:22144
	ds_read_b64_tr_b16 v[114:115], v89 offset:17600
	ds_read_b64_tr_b16 v[116:117], v89 offset:22208
	s_waitcnt lgkmcnt(9)
	v_cndmask_b32_e64 v101, v93, v87, s[6:7]
	v_cndmask_b32_e64 v100, v92, v86, s[6:7]
	v_cndmask_b32_e64 v99, v91, v85, s[6:7]
	v_cndmask_b32_e64 v98, v90, v84, s[6:7]
	v_cndmask_b32_e64 v87, v93, v87, s[4:5]
	v_cndmask_b32_e64 v86, v92, v86, s[4:5]
	s_waitcnt lgkmcnt(6)
	v_mfma_f32_32x32x16_bf16 v[64:79], v[102:105], v[98:101], v[64:79]
	ds_read_b64_tr_b16 v[102:103], v89 offset:26624
	ds_read_b64_tr_b16 v[104:105], v89 offset:31232
	v_cndmask_b32_e64 v85, v91, v85, s[4:5]
	v_cndmask_b32_e64 v84, v90, v84, s[4:5]
	s_waitcnt lgkmcnt(6)
	v_mfma_f32_32x32x16_bf16 v[48:63], v[106:109], v[98:101], v[48:63]
	ds_read_b64_tr_b16 v[106:107], v89 offset:26688
	ds_read_b64_tr_b16 v[108:109], v89 offset:31296
	s_waitcnt lgkmcnt(6)
	v_mfma_f32_32x32x16_bf16 v[32:47], v[110:113], v[98:101], v[32:47]
	ds_read_b64_tr_b16 v[110:111], v89 offset:26752
	ds_read_b64_tr_b16 v[112:113], v89 offset:31360
	s_waitcnt lgkmcnt(6)
	v_mfma_f32_32x32x16_bf16 v[16:31], v[114:117], v[98:101], v[16:31]
	ds_read_b64_tr_b16 v[114:115], v89 offset:26816
	ds_read_b64_tr_b16 v[116:117], v89 offset:31424
	v_cndmask_b32_e64 v101, v97, v83, s[6:7]
	v_cndmask_b32_e64 v100, v96, v82, s[6:7]
	v_cndmask_b32_e64 v99, v95, v81, s[6:7]
	v_cndmask_b32_e64 v98, v94, v80, s[6:7]
	v_cndmask_b32_e64 v83, v97, v83, s[4:5]
	v_cndmask_b32_e64 v82, v96, v82, s[4:5]
	s_waitcnt lgkmcnt(6)
	v_mfma_f32_32x32x16_bf16 v[64:79], v[102:105], v[98:101], v[64:79]
	ds_read_b64_tr_b16 v[102:103], v89 offset:35840
	ds_read_b64_tr_b16 v[104:105], v89 offset:40448
	v_cndmask_b32_e64 v81, v95, v81, s[4:5]
	v_cndmask_b32_e64 v80, v94, v80, s[4:5]
	s_waitcnt lgkmcnt(6)
	v_mfma_f32_32x32x16_bf16 v[48:63], v[106:109], v[98:101], v[48:63]
	ds_read_b64_tr_b16 v[106:107], v89 offset:35904
	ds_read_b64_tr_b16 v[108:109], v89 offset:40512
	s_waitcnt lgkmcnt(6)
	v_mfma_f32_32x32x16_bf16 v[32:47], v[110:113], v[98:101], v[32:47]
	ds_read_b64_tr_b16 v[110:111], v89 offset:35968
	ds_read_b64_tr_b16 v[112:113], v89 offset:40576
	s_waitcnt lgkmcnt(6)
	v_mfma_f32_32x32x16_bf16 v[16:31], v[114:117], v[98:101], v[16:31]
	ds_read_b64_tr_b16 v[90:91], v89 offset:36032
	ds_read_b64_tr_b16 v[92:93], v89 offset:40640
	s_waitcnt lgkmcnt(6)
	v_mfma_f32_32x32x16_bf16 v[64:79], v[102:105], v[84:87], v[64:79]
	ds_read_b64_tr_b16 v[98:99], v89 offset:45056
	ds_read_b64_tr_b16 v[100:101], v89 offset:49664
	s_waitcnt lgkmcnt(6)
	v_mfma_f32_32x32x16_bf16 v[48:63], v[106:109], v[84:87], v[48:63]
	ds_read_b64_tr_b16 v[102:103], v89 offset:45120
	ds_read_b64_tr_b16 v[104:105], v89 offset:49728
	s_waitcnt lgkmcnt(6)
	v_mfma_f32_32x32x16_bf16 v[32:47], v[110:113], v[84:87], v[32:47]
	ds_read_b64_tr_b16 v[106:107], v89 offset:45184
	ds_read_b64_tr_b16 v[108:109], v89 offset:49792
	s_waitcnt lgkmcnt(6)
	v_mfma_f32_32x32x16_bf16 v[16:31], v[90:93], v[84:87], v[16:31]
	ds_read_b64_tr_b16 v[84:85], v89 offset:45248
	ds_read_b64_tr_b16 v[86:87], v89 offset:49856
	s_waitcnt lgkmcnt(6)
	v_mfma_f32_32x32x16_bf16 v[64:79], v[98:101], v[80:83], v[64:79]
	s_waitcnt lgkmcnt(4)
	v_mfma_f32_32x32x16_bf16 v[48:63], v[102:105], v[80:83], v[48:63]
	s_waitcnt lgkmcnt(2)
	v_mfma_f32_32x32x16_bf16 v[32:47], v[106:109], v[80:83], v[32:47]
	s_waitcnt lgkmcnt(0)
	v_mfma_f32_32x32x16_bf16 v[16:31], v[84:87], v[80:83], v[16:31]
	s_setprio 0
	s_branch .LBB0_614

; #define LAS __attribute__((address_space(3)))
; __global__ void __launch_bounds__(512, 2) mega(Params p_unused) {
;     KQ kp = (KQ)__builtin_amdgcn_kernarg_segment_ptr();
;     extern __shared__ __attribute__((aligned(16))) unsigned char lds_raw[];
;     LAS unsigned char* lds = (LAS unsigned char*)lds_raw;
;     cg::grid_group grid = cg::this_grid();
;     LAS int* item_slot = (LAS int*)(lds + ITEM_OFF);
	.amdhsa_kernel _Z4mega6Params
		.amdhsa_group_segment_fixed_size 16384
		.amdhsa_private_segment_fixed_size 0
		.amdhsa_kernarg_size 400
		.amdhsa_user_sgpr_count 2
		.amdhsa_user_sgpr_dispatch_ptr 0
		.amdhsa_user_sgpr_queue_ptr 0
		.amdhsa_user_sgpr_kernarg_segment_ptr 1
		.amdhsa_user_sgpr_dispatch_id 0
		.amdhsa_user_sgpr_kernarg_preload_length 0
		.amdhsa_user_sgpr_kernarg_preload_offset 0
		.amdhsa_user_sgpr_private_segment_size 0
		.amdhsa_uses_dynamic_stack 0
		.amdhsa_enable_private_segment 0
		.amdhsa_system_sgpr_workgroup_id_x 1
		.amdhsa_system_sgpr_workgroup_id_y 0
		.amdhsa_system_sgpr_workgroup_id_z 0
		.amdhsa_system_sgpr_workgroup_info 0
		.amdhsa_system_vgpr_workitem_id 2
		.amdhsa_next_free_vgpr 256
		.amdhsa_next_free_sgpr 102
		.amdhsa_accum_offset 256
		.amdhsa_reserve_vcc 1
		.amdhsa_float_round_mode_32 0
		.amdhsa_float_round_mode_16_64 0
		.amdhsa_float_denorm_mode_32 3
		.amdhsa_float_denorm_mode_16_64 3
		.amdhsa_dx10_clamp 1
		.amdhsa_ieee_mode 1
		.amdhsa_fp16_overflow 0
		.amdhsa_tg_split 0
		.amdhsa_exception_fp_ieee_invalid_op 0
		.amdhsa_exception_fp_denorm_src 0
		.amdhsa_exception_fp_ieee_div_zero 0
		.amdhsa_exception_fp_ieee_overflow 0
		.amdhsa_exception_fp_ieee_underflow 0
		.amdhsa_exception_fp_ieee_inexact 0
		.amdhsa_exception_int_div_zero 0
	.end_amdhsa_kernel

; #define LAS __attribute__((address_space(3)))
; __global__ void __launch_bounds__(512, 2) mega(Params p_unused) {
;     KQ kp = (KQ)__builtin_amdgcn_kernarg_segment_ptr();
;     extern __shared__ __attribute__((aligned(16))) unsigned char lds_raw[];
;     LAS unsigned char* lds = (LAS unsigned char*)lds_raw;
;     cg::grid_group grid = cg::this_grid();
;     LAS int* item_slot = (LAS int*)(lds + ITEM_OFF);
amdhsa.kernels:
  - .agpr_count:     0
    .args:
      - .offset:         0
        .size:           144
        .value_kind:     by_value
      - .offset:         144
        .size:           4
        .value_kind:     hidden_block_count_x
      - .offset:         148
        .size:           4
        .value_kind:     hidden_block_count_y
      - .offset:         152
        .size:           4
        .value_kind:     hidden_block_count_z
      - .offset:         156
        .size:           2
        .value_kind:     hidden_group_size_x
      - .offset:         158
        .size:           2
        .value_kind:     hidden_group_size_y
      - .offset:         160
        .size:           2
        .value_kind:     hidden_group_size_z
      - .offset:         162
        .size:           2
        .value_kind:     hidden_remainder_x
      - .offset:         164
        .size:           2
        .value_kind:     hidden_remainder_y
      - .offset:         166
        .size:           2
        .value_kind:     hidden_remainder_z
      - .offset:         184
        .size:           8
        .value_kind:     hidden_global_offset_x
      - .offset:         192
        .size:           8
        .value_kind:     hidden_global_offset_y
      - .offset:         200
        .size:           8
        .value_kind:     hidden_global_offset_z
      - .offset:         208
        .size:           2
        .value_kind:     hidden_grid_dims
      - .offset:         232
        .size:           8
        .value_kind:     hidden_multigrid_sync_arg
      - .offset:         264
        .size:           4
        .value_kind:     hidden_dynamic_lds_size
    .group_segment_fixed_size: 16384
    .kernarg_segment_align: 8
    .kernarg_segment_size: 400
    .language:       OpenCL C
    .language_version:
      - 2
      - 0
    .max_flat_workgroup_size: 512
    .name:           _Z4mega6Params
    .private_segment_fixed_size: 0
    .sgpr_count:     108
    .sgpr_spill_count: 0
    .symbol:         _Z4mega6Params.kd
    .uniform_work_group_size: 1
    .uses_dynamic_stack: false
    .vgpr_count:     256
    .vgpr_spill_count: 0
    .wavefront_size: 64
